# Griffin: dead copy-back movs deleted + gate->scan block barrier removed (wave-local) on top of LDS-staged conv inputs
# speedup vs baseline: 1.0254x; 1.0004x over previous
.LBB0_486:
	s_waitcnt lgkmcnt(14)
	ds_read_b128 v[126:129], v235 offset:8320
	ds_read_b128 v[94:97], v235 offset:8336
	ds_read_b128 v[74:77], v235 offset:8352
	ds_read_b128 v[66:69], v235 offset:8368
	ds_read_b128 v[130:133], v235 offset:9344
	ds_read_b128 v[110:113], v235 offset:9360
	s_waitcnt lgkmcnt(14)
	ds_read_b128 v[134:137], v235 offset:8576
	ds_read_b128 v[114:117], v235 offset:8592
	ds_read_b128 v[138:141], v235 offset:8832
	ds_read_b128 v[118:121], v235 offset:8848
	ds_read_b128 v[142:145], v235 offset:9088
	ds_read_b128 v[122:125], v235 offset:9104
	s_waitcnt lgkmcnt(14)
	ds_read_b128 v[90:93], v235 offset:9376
	ds_read_b128 v[70:73], v235 offset:9392
	ds_read_b128 v[98:101], v235 offset:8608
	ds_read_b128 v[78:81], v235 offset:8624
	ds_read_b128 v[102:105], v235 offset:8864
	ds_read_b128 v[82:85], v235 offset:8880
	s_waitcnt lgkmcnt(14)
	ds_read_b128 v[106:109], v235 offset:9120
	ds_read_b128 v[86:89], v235 offset:9136
	s_add_i32 s45, s16, 1
	s_cmp_eq_u32 s16, 63
	s_cbranch_scc1 .LBB0_520
	s_lshl_b32 s28, s45, 6
	s_add_i32 s28, s28, -3
	s_ashr_i32 s29, s28, 31
	s_lshl_b64 s[28:29], s[28:29], 11
	v_lshl_add_u64 v[224:225], v[158:159], 0, s[28:29]
	s_cmp_lg_u32 s45, 0
	s_cselect_b64 s[28:29], -1, 0
	v_cmp_lt_u32_e32 vcc, 2, v233
	v_mov_b32_e32 v2, 0
	v_mov_b32_e32 v3, 0
	v_mov_b32_e32 v4, 0
	v_mov_b32_e32 v5, 0
	s_or_b64 s[28:29], s[28:29], vcc
	s_mov_b32 s30, 0x8000
	s_mov_b32 s31, 0
	s_and_saveexec_b64 s[34:35], s[28:29]
	s_cbranch_execz .Lgx_l0
	global_load_dwordx4 v[2:5], v[224:225], off
